# v24 + the five GEMM K-loop heads aligned to 64 bytes (unreachable padding)
# baseline (speedup 1.0000x reference)
; #define PG8_STAGE(bufoff, gbase, voff) do { _Pragma("unroll") for (int _i = 0; _i < 2; ++_i) \
;         __builtin_amdgcn_global_load_lds((const unsigned*)((const char*)(gbase) + (voff)[_i]), (PG8_LAS unsigned*)(lds + (bufoff) + ldsw + _i * 8192), 16, 0, 0); } while (0)
; #define PG8_LDA(dst, b, h) do { _Pragma("unroll") for (int m = 0; m < 4; ++m) _Pragma("unroll") for (int k = 0; k < 2; ++k) dst[m][k] = *(const PG8_LAS bf16x8*)(lds + PG8_SA(b, h) + aoff + m * 2048 + k * 1024); } while (0)
; #define PG8_LDB(dst, b, h) do { _Pragma("unroll") for (int n = 0; n < 2; ++n) _Pragma("unroll") for (int k = 0; k < 2; ++k) dst[n][k] = *(const PG8_LAS bf16x8*)(lds + PG8_SB(b, h) + boff + n * 2048 + k * 1024); } while (0)
; #define PG8_WAIT_V(n) asm volatile("s_waitcnt vmcnt(" #n ")" ::: "memory")
; #define PG8_WAIT_L(n) asm volatile("s_waitcnt lgkmcnt(" #n ")" ::: "memory")
; #define PG8_BAR __builtin_amdgcn_s_barrier()
; #define PG8_SCHED __builtin_amdgcn_sched_barrier(0)
;     __device__ __forceinline__ void operator()(const f32x4 (&acc)[2][2][4][2], const Unit& u, int wr, int wc, int fr, int fq) const {
;     ...
;                 float rsc = sc; if (rsmode == 1) { const float r_ = rs[row0 + ai * HALF + m * 16]; rsc = sc * (ACT == 2 ? r_ * r_ : r_); }
; template <class Epi, class Sched, bool ALIGN_EPI = false, bool SP2 = false>
; __device__ __forceinline__ void gemm_phase(PG8_LAS unsigned char* lds, const Gemm g, const Sched& S, const Epi& E) {
;     ...
;         const bool has_next = S.next(ui + 1, nxt);
;         const char* nA = has_next ? (const char*)g.A + (size_t)nxt.pm * tstep : cA; const char* nB = has_next ? (const char*)g.Bt + (size_t)nxt.pn * tstep : cB;
;         for (int t = 0; t < nt; t += 2) {
;             const bool last = (t == nt - 2);
;             const char* a1 = cA + (size_t)(t + 1) * kstep;
;             const char* a2 = last ? nA : cA + (size_t)(t + 2) * kstep; const char* b2 = last ? nB : cB + (size_t)(t + 2) * kstep;
;             const char* a3 = a2 + kstep; const char* b3 = b2 + kstep;
;             if (last && has_next) S.a_ready(nxt);
;             if constexpr (SP2) {
;             PG8_LDB(B0, 0, 0); PG8_LDB(B1, 0, 1); PG8_SCHED; PG8_LDA(At, 0, 0); PG8_STAGE(PG8_SA(1, 0), a1, voffA); PG8_STAGE(PG8_SA(1, 1), a1 + hstep, voffA);
;             PG8_WAIT_V(8); PG8_WAIT_L(0); PG8_BAR; PG8_MMA(0, 0, At, B0); PG8_MMA(0, 1, At, B1); PG8_BAR; PG8_SCHED;
.LBB0_211:
	s_ashr_i32 s89, s88, 31
	s_lshl_b64 s[4:5], s[88:89], 20
	s_add_u32 s4, s22, s4
	s_addc_u32 s5, s75, s5
	s_and_b64 s[6:7], s[38:39], exec
	s_cselect_b32 s89, s5, s9
	s_cselect_b32 vcc_lo, s4, s8
	s_ashr_i32 s73, s72, 31
	s_lshl_b64 s[6:7], s[72:73], 20
	s_add_u32 s6, s68, s6
	s_addc_u32 s7, s69, s7
	s_and_b64 s[16:17], s[38:39], exec
	s_cselect_b32 s70, s7, s11
	s_cselect_b32 s71, s6, s10
	s_add_u32 s73, s10, 0x100
	s_addc_u32 vcc_hi, s11, 0
	s_mov_b32 s52, -2
	s_mov_b64 s[10:11], 0
	v_lshl_add_u64 v[138:139], s[8:9], 0, v[134:135]
	v_lshl_add_u64 v[140:141], s[8:9], 0, v[136:137]
	v_lshl_add_u32 v240, s35, 8, v146
	v_ashrrev_i32_e32 v241, 31, v240
	v_lshl_add_u64 v[240:241], v[240:241], 2, s[42:43]
	global_load_dword v242, v[240:241], off
	global_load_dword v243, v[240:241], off offset:64
	global_load_dword v244, v[240:241], off offset:128
	global_load_dword v245, v[240:241], off offset:192
	global_load_dword v246, v[240:241], off offset:512
	global_load_dword v247, v[240:241], off offset:576
	global_load_dword v248, v[240:241], off offset:640
	global_load_dword v249, v[240:241], off offset:704
	s_add_u32 s16, s8, s10
	s_addc_u32 s17, s9, s11
	s_add_u32 s44, s16, 0x100
	s_addc_u32 s45, s17, 0
	s_add_u32 s16, s73, s10
	s_addc_u32 s17, vcc_hi, s11
	s_add_i32 s53, 0, 0x10000
	s_cmpk_eq_i32 s10, 0xf00
	s_cselect_b32 s17, s70, s17
	s_cselect_b32 s16, s71, s16
	s_cselect_b32 s45, s89, s45
	s_cselect_b32 s44, vcc_lo, s44
	s_add_i32 s92, 0, 0x14000
	v_add_u32_e32 v158, s53, v147
	ds_read_b128 v[142:145], v158
	ds_read_b128 v[150:153], v158 offset:1024
	ds_read_b128 v[154:157], v158 offset:2048
	ds_read_b128 v[158:161], v158 offset:3072
	v_lshl_add_u64 v[202:203], v[138:139], 0, s[10:11]
	v_lshl_add_u64 v[206:207], v[202:203], 0, s[26:27]
	s_add_i32 m0, s97, 0x8000
	global_load_lds_dwordx4 v[206:207], off
	v_lshl_add_u64 v[206:207], v[140:141], 0, s[10:11]
	v_lshl_add_u64 v[208:209], v[206:207], 0, s[26:27]
	s_add_i32 m0, s97, 0xa000
	v_lshl_add_u64 v[202:203], v[202:203], 0, s[28:29]
	global_load_lds_dwordx4 v[208:209], off
	s_add_i32 m0, s97, 0xc000
	s_nop 0
	global_load_lds_dwordx4 v[202:203], off
	v_lshl_add_u64 v[202:203], v[206:207], 0, s[28:29]
	s_add_i32 m0, s97, 0xe000
	s_nop 0
	global_load_lds_dwordx4 v[202:203], off
	s_waitcnt vmcnt(8)
	s_waitcnt lgkmcnt(0)
	s_barrier
	v_mfma_f32_16x16x32_bf16 v[124:127], v[142:145], v[178:181], 0
	v_mfma_f32_16x16x32_bf16 v[120:123], v[154:157], v[178:181], 0
	v_mfma_f32_16x16x32_bf16 v[108:111], v[142:145], v[186:189], 0
	v_mfma_f32_16x16x32_bf16 v[104:107], v[154:157], v[186:189], 0
	v_mfma_f32_16x16x32_bf16 v[92:95], v[142:145], v[194:197], 0
	v_mfma_f32_16x16x32_bf16 v[88:91], v[154:157], v[194:197], 0
	v_mfma_f32_16x16x32_bf16 v[76:79], v[142:145], v[218:221], 0
	v_mfma_f32_16x16x32_bf16 v[72:75], v[154:157], v[218:221], 0
	v_mfma_f32_16x16x32_bf16 v[124:127], v[150:153], v[182:185], v[124:127]
	v_mfma_f32_16x16x32_bf16 v[120:123], v[158:161], v[182:185], v[120:123]
	v_mfma_f32_16x16x32_bf16 v[108:111], v[150:153], v[190:193], v[108:111]
	v_mfma_f32_16x16x32_bf16 v[104:107], v[158:161], v[190:193], v[104:107]
	v_mfma_f32_16x16x32_bf16 v[92:95], v[150:153], v[198:201], v[92:95]
	v_mfma_f32_16x16x32_bf16 v[88:91], v[158:161], v[198:201], v[88:91]
	v_mfma_f32_16x16x32_bf16 v[76:79], v[150:153], v[232:235], v[76:79]
	v_mfma_f32_16x16x32_bf16 v[72:75], v[158:161], v[232:235], v[72:75]
	v_mfma_f32_16x16x32_bf16 v[116:119], v[162:165], v[178:181], 0
	v_mfma_f32_16x16x32_bf16 v[112:115], v[170:173], v[178:181], 0
	v_mfma_f32_16x16x32_bf16 v[100:103], v[162:165], v[186:189], 0
	v_mfma_f32_16x16x32_bf16 v[96:99], v[170:173], v[186:189], 0
	v_mfma_f32_16x16x32_bf16 v[84:87], v[162:165], v[194:197], 0
	v_mfma_f32_16x16x32_bf16 v[80:83], v[170:173], v[194:197], 0
	v_mfma_f32_16x16x32_bf16 v[68:71], v[162:165], v[218:221], 0
	v_mfma_f32_16x16x32_bf16 v[64:67], v[170:173], v[218:221], 0
	v_mfma_f32_16x16x32_bf16 v[116:119], v[166:169], v[182:185], v[116:119]
	v_mfma_f32_16x16x32_bf16 v[112:115], v[174:177], v[182:185], v[112:115]
	v_mfma_f32_16x16x32_bf16 v[100:103], v[166:169], v[190:193], v[100:103]
	v_mfma_f32_16x16x32_bf16 v[96:99], v[174:177], v[190:193], v[96:99]
	v_mfma_f32_16x16x32_bf16 v[84:87], v[166:169], v[198:201], v[84:87]
	v_mfma_f32_16x16x32_bf16 v[80:83], v[174:177], v[198:201], v[80:83]
	v_mfma_f32_16x16x32_bf16 v[68:71], v[166:169], v[232:235], v[68:71]
	v_mfma_f32_16x16x32_bf16 v[64:67], v[174:177], v[232:235], v[64:67]
	s_barrier
; #define PG8_STAGE(bufoff, gbase, voff) do { _Pragma("unroll") for (int _i = 0; _i < 2; ++_i) \
;         __builtin_amdgcn_global_load_lds((const unsigned*)((const char*)(gbase) + (voff)[_i]), (PG8_LAS unsigned*)(lds + (bufoff) + ldsw + _i * 8192), 16, 0, 0); } while (0)
; #define PG8_LDA(dst, b, h) do { _Pragma("unroll") for (int m = 0; m < 4; ++m) _Pragma("unroll") for (int k = 0; k < 2; ++k) dst[m][k] = *(const PG8_LAS bf16x8*)(lds + PG8_SA(b, h) + aoff + m * 2048 + k * 1024); } while (0)
; #define PG8_MMA(ai, bj, At, Bt) do { __builtin_amdgcn_s_setprio(1); _Pragma("unroll") for (int m = 0; m < 4; ++m) _Pragma("unroll") for (int n = 0; n < 2; ++n) _Pragma("unroll") for (int k = 0; k < 2; ++k) \
;         acc[ai][bj][m][n] = __builtin_amdgcn_mfma_f32_16x16x32_bf16(Bt[n][k], At[m][k], acc[ai][bj][m][n], 0, 0, 0); __builtin_amdgcn_s_setprio(0); } while (0)
; #define PG8_WAIT_V(n) asm volatile("s_waitcnt vmcnt(" #n ")" ::: "memory")
; #define PG8_WAIT_L(n) asm volatile("s_waitcnt lgkmcnt(" #n ")" ::: "memory")
; #define PG8_BAR __builtin_amdgcn_s_barrier()
; #define PG8_SCHED __builtin_amdgcn_sched_barrier(0)
; template <class Epi, class Sched, bool ALIGN_EPI = false, bool SP2 = false>
; __device__ __forceinline__ void gemm_phase(PG8_LAS unsigned char* lds, const Gemm g, const Sched& S, const Epi& E) {
;     ...
;             PG8_LDA(At, 0, 1); PG8_STAGE(PG8_SB(0, 0), b2, voffB); PG8_STAGE(PG8_SB(0, 1), b2 + hstep, voffB);
;             PG8_WAIT_V(6); PG8_WAIT_L(0); PG8_BAR; PG8_MMA(1, 0, At, B0); PG8_MMA(1, 1, At, B1); PG8_BAR; PG8_SCHED;
	s_add_i32 s53, s53, s23
	v_lshl_add_u64 v[202:203], s[16:17], 0, v[204:205]
	s_mov_b32 m0, s53
	ds_read_b128 v[178:181], v149 offset:16384
	ds_read_b128 v[182:185], v149 offset:17408
	ds_read_b128 v[186:189], v149 offset:18432
	ds_read_b128 v[190:193], v149 offset:19456
	ds_read_b128 v[194:197], v149 offset:20480
	ds_read_b128 v[198:201], v149 offset:21504
	ds_read_b128 v[218:221], v149 offset:22528
	ds_read_b128 v[232:235], v149 offset:23552
	global_load_lds_dwordx4 v[202:203], off
	s_add_i32 m0, s53, 0x2000
	s_add_u32 s78, s16, 0x80000
	v_lshl_add_u64 v[206:207], s[16:17], 0, v[128:129]
	s_addc_u32 s79, s17, 0
	s_add_i32 s53, s92, s23
	global_load_lds_dwordx4 v[206:207], off
	v_lshl_add_u64 v[208:209], s[78:79], 0, v[204:205]
	s_mov_b32 m0, s53
	s_nop 0
	global_load_lds_dwordx4 v[208:209], off
	v_lshl_add_u64 v[208:209], s[78:79], 0, v[128:129]
	s_add_i32 m0, s53, 0x2000
	s_nop 0
	global_load_lds_dwordx4 v[208:209], off
	s_waitcnt vmcnt(6)
	s_waitcnt lgkmcnt(0)
	s_barrier
	v_mfma_f32_16x16x32_bf16 v[60:63], v[142:145], v[178:181], 0
	v_mfma_f32_16x16x32_bf16 v[56:59], v[154:157], v[178:181], 0
	v_mfma_f32_16x16x32_bf16 v[44:47], v[142:145], v[186:189], 0
	v_mfma_f32_16x16x32_bf16 v[40:43], v[154:157], v[186:189], 0
	v_mfma_f32_16x16x32_bf16 v[28:31], v[142:145], v[194:197], 0
	v_mfma_f32_16x16x32_bf16 v[24:27], v[154:157], v[194:197], 0
	v_mfma_f32_16x16x32_bf16 v[12:15], v[142:145], v[218:221], 0
	v_mfma_f32_16x16x32_bf16 v[8:11], v[154:157], v[218:221], 0
	v_mfma_f32_16x16x32_bf16 v[60:63], v[150:153], v[182:185], v[60:63]
	v_mfma_f32_16x16x32_bf16 v[56:59], v[158:161], v[182:185], v[56:59]
	v_mfma_f32_16x16x32_bf16 v[44:47], v[150:153], v[190:193], v[44:47]
	v_mfma_f32_16x16x32_bf16 v[40:43], v[158:161], v[190:193], v[40:43]
	v_mfma_f32_16x16x32_bf16 v[28:31], v[150:153], v[198:201], v[28:31]
	v_mfma_f32_16x16x32_bf16 v[24:27], v[158:161], v[198:201], v[24:27]
	v_mfma_f32_16x16x32_bf16 v[12:15], v[150:153], v[232:235], v[12:15]
	v_mfma_f32_16x16x32_bf16 v[8:11], v[158:161], v[232:235], v[8:11]
	v_mfma_f32_16x16x32_bf16 v[52:55], v[162:165], v[178:181], 0
	v_mfma_f32_16x16x32_bf16 v[48:51], v[170:173], v[178:181], 0
	v_mfma_f32_16x16x32_bf16 v[36:39], v[162:165], v[186:189], 0
	v_mfma_f32_16x16x32_bf16 v[32:35], v[170:173], v[186:189], 0
	v_mfma_f32_16x16x32_bf16 v[20:23], v[162:165], v[194:197], 0
	v_mfma_f32_16x16x32_bf16 v[16:19], v[170:173], v[194:197], 0
	v_mfma_f32_16x16x32_bf16 v[4:7], v[162:165], v[218:221], 0
	v_mfma_f32_16x16x32_bf16 v[0:3], v[170:173], v[218:221], 0
	v_mfma_f32_16x16x32_bf16 v[52:55], v[166:169], v[182:185], v[52:55]
	v_mfma_f32_16x16x32_bf16 v[48:51], v[174:177], v[182:185], v[48:51]
	v_mfma_f32_16x16x32_bf16 v[36:39], v[166:169], v[190:193], v[36:39]
	v_mfma_f32_16x16x32_bf16 v[32:35], v[174:177], v[190:193], v[32:35]
	v_mfma_f32_16x16x32_bf16 v[20:23], v[166:169], v[198:201], v[20:23]
	v_mfma_f32_16x16x32_bf16 v[16:19], v[174:177], v[198:201], v[16:19]
	v_mfma_f32_16x16x32_bf16 v[4:7], v[166:169], v[232:235], v[4:7]
	v_mfma_f32_16x16x32_bf16 v[0:3], v[174:177], v[232:235], v[0:3]
	s_barrier
	s_branch .Lpl_qk
	.p2align 6

; #define PG8_STAGE(bufoff, gbase, voff) do { _Pragma("unroll") for (int _i = 0; _i < 2; ++_i) \
;         __builtin_amdgcn_global_load_lds((const unsigned*)((const char*)(gbase) + (voff)[_i]), (PG8_LAS unsigned*)(lds + (bufoff) + ldsw + _i * 8192), 16, 0, 0); } while (0)
; #define PG8_LDA(dst, b, h) do { _Pragma("unroll") for (int m = 0; m < 4; ++m) _Pragma("unroll") for (int k = 0; k < 2; ++k) dst[m][k] = *(const PG8_LAS bf16x8*)(lds + PG8_SA(b, h) + aoff + m * 2048 + k * 1024); } while (0)
; #define PG8_LDB(dst, b, h) do { _Pragma("unroll") for (int n = 0; n < 2; ++n) _Pragma("unroll") for (int k = 0; k < 2; ++k) dst[n][k] = *(const PG8_LAS bf16x8*)(lds + PG8_SB(b, h) + boff + n * 2048 + k * 1024); } while (0)
; #define PG8_MMA(ai, bj, At, Bt) do { __builtin_amdgcn_s_setprio(1); _Pragma("unroll") for (int m = 0; m < 4; ++m) _Pragma("unroll") for (int n = 0; n < 2; ++n) _Pragma("unroll") for (int k = 0; k < 2; ++k) \
;         acc[ai][bj][m][n] = __builtin_amdgcn_mfma_f32_16x16x32_bf16(Bt[n][k], At[m][k], acc[ai][bj][m][n], 0, 0, 0); __builtin_amdgcn_s_setprio(0); } while (0)
; #define PG8_WAIT_V(n) asm volatile("s_waitcnt vmcnt(" #n ")" ::: "memory")
; #define PG8_WAIT_L(n) asm volatile("s_waitcnt lgkmcnt(" #n ")" ::: "memory")
; template <class Epi, class Sched, bool ALIGN_EPI = false, bool SP2 = false>
; __device__ __forceinline__ void gemm_phase(PG8_LAS unsigned char* lds, const Gemm g, const Sched& S, const Epi& E) {
;     ...
;         const bool has_next = S.next(ui + 1, nxt);
;         const char* nA = has_next ? (const char*)g.A + (size_t)nxt.pm * tstep : cA; const char* nB = has_next ? (const char*)g.Bt + (size_t)nxt.pn * tstep : cB;
;         for (int t = 0; t < nt; t += 2) {
;             const bool last = (t == nt - 2);
;             const char* a1 = cA + (size_t)(t + 1) * kstep;
;             const char* a2 = last ? nA : cA + (size_t)(t + 2) * kstep; const char* b2 = last ? nB : cB + (size_t)(t + 2) * kstep;
;             const char* a3 = a2 + kstep; const char* b3 = b2 + kstep;
;             if (last && has_next) S.a_ready(nxt);
;             if constexpr (SP2) {
;             PG8_LDB(B0, 0, 0); PG8_LDB(B1, 0, 1); PG8_SCHED; PG8_LDA(At, 0, 0); PG8_STAGE(PG8_SA(1, 0), a1, voffA); PG8_STAGE(PG8_SA(1, 1), a1 + hstep, voffA);
;             PG8_WAIT_V(8); PG8_WAIT_L(0); PG8_BAR; PG8_MMA(0, 0, At, B0); PG8_MMA(0, 1, At, B1); PG8_BAR; PG8_SCHED;
.LBB0_231:
	s_ashr_i32 s47, s46, 31
	s_lshl_b64 s[52:53], s[46:47], 20
	s_add_u32 s72, s20, s52
	s_addc_u32 s73, s21, s53
	s_and_b64 s[52:53], s[38:39], exec
	s_cselect_b32 s47, s73, s17
	s_cselect_b32 s68, s72, s16
	s_ashr_i32 s11, s10, 31
	s_lshl_b64 s[52:53], s[10:11], 20
	s_add_u32 s76, s22, s52
	s_addc_u32 s77, s75, s53
	s_and_b64 s[52:53], s[38:39], exec
	s_cselect_b32 s11, s77, s45
	s_cselect_b32 s69, s76, s44
	s_add_u32 s70, s44, 0x100
	s_addc_u32 s71, s45, 0
	v_lshl_add_u64 v[96:97], s[16:17], 0, v[150:151]
	v_lshl_add_u64 v[98:99], s[16:17], 0, v[152:153]
	s_mov_b32 s52, -2
	s_mov_b64 s[88:89], 0
	s_add_u32 s44, s16, s88
	s_addc_u32 s45, s17, s89
	s_add_u32 s53, s44, 0x100
	s_addc_u32 s78, s45, 0
	s_add_u32 s44, s70, s88
	s_addc_u32 s45, s71, s89
	s_add_i32 s79, 0, 0x10000
	s_cmpk_eq_i32 s88, 0xf00
	s_cselect_b32 s45, s11, s45
	s_cselect_b32 s44, s69, s44
	s_cselect_b32 s95, s47, s78
	s_cselect_b32 s94, s68, s53
	s_add_i32 s53, 0, 0x14000
	v_add_u32_e32 v154, s79, v161
	v_add_u32_e32 v158, s53, v161
	ds_read_b128 v[100:103], v154
	ds_read_b128 v[104:107], v154 offset:1024
	ds_read_b128 v[108:111], v154 offset:2048
	ds_read_b128 v[154:157], v154 offset:3072
	ds_read_b128 v[164:167], v158
	ds_read_b128 v[168:171], v158 offset:1024
	ds_read_b128 v[172:175], v158 offset:2048
	ds_read_b128 v[176:179], v158 offset:3072
	v_lshl_add_u64 v[158:159], v[96:97], 0, s[88:89]
	v_lshl_add_u64 v[206:207], v[158:159], 0, s[26:27]
	s_add_i32 m0, s57, 0x8000
	global_load_lds_dwordx4 v[206:207], off
	v_lshl_add_u64 v[206:207], v[98:99], 0, s[88:89]
	v_lshl_add_u64 v[208:209], v[206:207], 0, s[26:27]
	s_add_i32 m0, s57, 0xa000
	v_lshl_add_u64 v[158:159], v[158:159], 0, s[28:29]
	global_load_lds_dwordx4 v[208:209], off
	s_add_i32 m0, s57, 0xc000
	s_nop 0
	global_load_lds_dwordx4 v[158:159], off
	v_lshl_add_u64 v[158:159], v[206:207], 0, s[28:29]
	s_add_i32 m0, s57, 0xe000
	s_nop 0
	global_load_lds_dwordx4 v[158:159], off
	s_waitcnt vmcnt(8)
	s_waitcnt lgkmcnt(0)
	s_barrier
	v_mfma_f32_16x16x32_bf16 v[140:143], v[100:103], v[180:183], 0
	v_mfma_f32_16x16x32_bf16 v[136:139], v[108:111], v[180:183], 0
	v_mfma_f32_16x16x32_bf16 v[124:127], v[100:103], v[188:191], 0
	v_mfma_f32_16x16x32_bf16 v[120:123], v[108:111], v[188:191], 0
	v_mfma_f32_16x16x32_bf16 v[92:95], v[100:103], v[196:199], 0
	v_mfma_f32_16x16x32_bf16 v[88:91], v[108:111], v[196:199], 0
	v_mfma_f32_16x16x32_bf16 v[76:79], v[100:103], v[218:221], 0
	v_mfma_f32_16x16x32_bf16 v[72:75], v[108:111], v[218:221], 0
	v_mfma_f32_16x16x32_bf16 v[140:143], v[104:107], v[184:187], v[140:143]
	v_mfma_f32_16x16x32_bf16 v[136:139], v[154:157], v[184:187], v[136:139]
	v_mfma_f32_16x16x32_bf16 v[124:127], v[104:107], v[192:195], v[124:127]
	v_mfma_f32_16x16x32_bf16 v[120:123], v[154:157], v[192:195], v[120:123]
	v_mfma_f32_16x16x32_bf16 v[92:95], v[104:107], v[200:203], v[92:95]
	v_mfma_f32_16x16x32_bf16 v[88:91], v[154:157], v[200:203], v[88:91]
	v_mfma_f32_16x16x32_bf16 v[76:79], v[104:107], v[232:235], v[76:79]
	v_mfma_f32_16x16x32_bf16 v[72:75], v[154:157], v[232:235], v[72:75]
	v_mfma_f32_16x16x32_bf16 v[132:135], v[164:167], v[180:183], 0
	v_mfma_f32_16x16x32_bf16 v[128:131], v[172:175], v[180:183], 0
	v_mfma_f32_16x16x32_bf16 v[116:119], v[164:167], v[188:191], 0
	v_mfma_f32_16x16x32_bf16 v[112:115], v[172:175], v[188:191], 0
	v_mfma_f32_16x16x32_bf16 v[84:87], v[164:167], v[196:199], 0
	v_mfma_f32_16x16x32_bf16 v[80:83], v[172:175], v[196:199], 0
	v_mfma_f32_16x16x32_bf16 v[68:71], v[164:167], v[218:221], 0
	v_mfma_f32_16x16x32_bf16 v[64:67], v[172:175], v[218:221], 0
	v_mfma_f32_16x16x32_bf16 v[132:135], v[168:171], v[184:187], v[132:135]
	v_mfma_f32_16x16x32_bf16 v[128:131], v[176:179], v[184:187], v[128:131]
	v_mfma_f32_16x16x32_bf16 v[116:119], v[168:171], v[192:195], v[116:119]
	v_mfma_f32_16x16x32_bf16 v[112:115], v[176:179], v[192:195], v[112:115]
	v_mfma_f32_16x16x32_bf16 v[84:87], v[168:171], v[200:203], v[84:87]
	v_mfma_f32_16x16x32_bf16 v[80:83], v[176:179], v[200:203], v[80:83]
	v_mfma_f32_16x16x32_bf16 v[68:71], v[168:171], v[232:235], v[68:71]
	v_mfma_f32_16x16x32_bf16 v[64:67], v[176:179], v[232:235], v[64:67]
	s_barrier
; #define PG8_STAGE(bufoff, gbase, voff) do { _Pragma("unroll") for (int _i = 0; _i < 2; ++_i) \
;         __builtin_amdgcn_global_load_lds((const unsigned*)((const char*)(gbase) + (voff)[_i]), (PG8_LAS unsigned*)(lds + (bufoff) + ldsw + _i * 8192), 16, 0, 0); } while (0)
; #define PG8_LDA(dst, b, h) do { _Pragma("unroll") for (int m = 0; m < 4; ++m) _Pragma("unroll") for (int k = 0; k < 2; ++k) dst[m][k] = *(const PG8_LAS bf16x8*)(lds + PG8_SA(b, h) + aoff + m * 2048 + k * 1024); } while (0)
; #define PG8_MMA(ai, bj, At, Bt) do { __builtin_amdgcn_s_setprio(1); _Pragma("unroll") for (int m = 0; m < 4; ++m) _Pragma("unroll") for (int n = 0; n < 2; ++n) _Pragma("unroll") for (int k = 0; k < 2; ++k) \
;         acc[ai][bj][m][n] = __builtin_amdgcn_mfma_f32_16x16x32_bf16(Bt[n][k], At[m][k], acc[ai][bj][m][n], 0, 0, 0); __builtin_amdgcn_s_setprio(0); } while (0)
; #define PG8_WAIT_V(n) asm volatile("s_waitcnt vmcnt(" #n ")" ::: "memory")
; #define PG8_WAIT_L(n) asm volatile("s_waitcnt lgkmcnt(" #n ")" ::: "memory")
; #define PG8_BAR __builtin_amdgcn_s_barrier()
; #define PG8_SCHED __builtin_amdgcn_sched_barrier(0)
; template <class Epi, class Sched, bool ALIGN_EPI = false, bool SP2 = false>
; __device__ __forceinline__ void gemm_phase(PG8_LAS unsigned char* lds, const Gemm g, const Sched& S, const Epi& E) {
;     ...
;             PG8_LDA(At, 0, 1); PG8_STAGE(PG8_SB(0, 0), b2, voffB); PG8_STAGE(PG8_SB(0, 1), b2 + hstep, voffB);
;             PG8_WAIT_V(6); PG8_WAIT_L(0); PG8_BAR; PG8_MMA(1, 0, At, B0); PG8_MMA(1, 1, At, B1); PG8_BAR; PG8_SCHED;
	s_add_i32 s78, s79, s23
	v_lshl_add_u64 v[158:159], s[44:45], 0, v[204:205]
	s_mov_b32 m0, s78
	ds_read_b128 v[180:183], v163 offset:16384
	ds_read_b128 v[184:187], v163 offset:17408
	ds_read_b128 v[188:191], v163 offset:18432
	ds_read_b128 v[192:195], v163 offset:19456
	ds_read_b128 v[196:199], v163 offset:20480
	ds_read_b128 v[200:203], v163 offset:21504
	ds_read_b128 v[218:221], v163 offset:22528
	ds_read_b128 v[232:235], v163 offset:23552
	global_load_lds_dwordx4 v[158:159], off
	s_add_i32 m0, s78, 0x2000
	s_add_u32 s78, s44, 0x80000
	v_lshl_add_u64 v[206:207], s[44:45], 0, v[144:145]
	s_addc_u32 s79, s45, 0
	s_add_i32 s53, s53, s23
	global_load_lds_dwordx4 v[206:207], off
	v_lshl_add_u64 v[208:209], s[78:79], 0, v[204:205]
	s_mov_b32 m0, s53
	s_nop 0
	global_load_lds_dwordx4 v[208:209], off
	v_lshl_add_u64 v[208:209], s[78:79], 0, v[144:145]
	s_add_i32 m0, s53, 0x2000
	s_nop 0
	global_load_lds_dwordx4 v[208:209], off
	s_waitcnt vmcnt(6)
	s_waitcnt lgkmcnt(0)
	s_barrier
	v_mfma_f32_16x16x32_bf16 v[60:63], v[100:103], v[180:183], 0
	v_mfma_f32_16x16x32_bf16 v[56:59], v[108:111], v[180:183], 0
	v_mfma_f32_16x16x32_bf16 v[48:51], v[100:103], v[188:191], 0
	v_mfma_f32_16x16x32_bf16 v[40:43], v[108:111], v[188:191], 0
	v_mfma_f32_16x16x32_bf16 v[32:35], v[100:103], v[196:199], 0
	v_mfma_f32_16x16x32_bf16 v[24:27], v[108:111], v[196:199], 0
	v_mfma_f32_16x16x32_bf16 v[16:19], v[100:103], v[218:221], 0
	v_mfma_f32_16x16x32_bf16 v[8:11], v[108:111], v[218:221], 0
	v_mfma_f32_16x16x32_bf16 v[60:63], v[104:107], v[184:187], v[60:63]
	v_mfma_f32_16x16x32_bf16 v[56:59], v[154:157], v[184:187], v[56:59]
	v_mfma_f32_16x16x32_bf16 v[48:51], v[104:107], v[192:195], v[48:51]
	v_mfma_f32_16x16x32_bf16 v[40:43], v[154:157], v[192:195], v[40:43]
	v_mfma_f32_16x16x32_bf16 v[32:35], v[104:107], v[200:203], v[32:35]
	v_mfma_f32_16x16x32_bf16 v[24:27], v[154:157], v[200:203], v[24:27]
	v_mfma_f32_16x16x32_bf16 v[16:19], v[104:107], v[232:235], v[16:19]
	v_mfma_f32_16x16x32_bf16 v[8:11], v[154:157], v[232:235], v[8:11]
	v_mfma_f32_16x16x32_bf16 v[52:55], v[164:167], v[180:183], 0
	v_mfma_f32_16x16x32_bf16 v[44:47], v[172:175], v[180:183], 0
	v_mfma_f32_16x16x32_bf16 v[36:39], v[164:167], v[188:191], 0
	v_mfma_f32_16x16x32_bf16 v[28:31], v[172:175], v[188:191], 0
	v_mfma_f32_16x16x32_bf16 v[20:23], v[164:167], v[196:199], 0
	v_mfma_f32_16x16x32_bf16 v[12:15], v[172:175], v[196:199], 0
	v_mfma_f32_16x16x32_bf16 v[4:7], v[164:167], v[218:221], 0
	v_mfma_f32_16x16x32_bf16 v[0:3], v[172:175], v[218:221], 0
	v_mfma_f32_16x16x32_bf16 v[52:55], v[168:171], v[184:187], v[52:55]
	v_mfma_f32_16x16x32_bf16 v[44:47], v[176:179], v[184:187], v[44:47]
	v_mfma_f32_16x16x32_bf16 v[36:39], v[168:171], v[192:195], v[36:39]
	v_mfma_f32_16x16x32_bf16 v[28:31], v[176:179], v[192:195], v[28:31]
	v_mfma_f32_16x16x32_bf16 v[20:23], v[168:171], v[200:203], v[20:23]
	v_mfma_f32_16x16x32_bf16 v[12:15], v[176:179], v[200:203], v[12:15]
	v_mfma_f32_16x16x32_bf16 v[4:7], v[168:171], v[232:235], v[4:7]
	v_mfma_f32_16x16x32_bf16 v[0:3], v[176:179], v[232:235], v[0:3]
	s_barrier
	s_branch .Lpl_vt
	.p2align 6

; #define PG8_STAGE(bufoff, gbase, voff) do { _Pragma("unroll") for (int _i = 0; _i < 2; ++_i) \
;         __builtin_amdgcn_global_load_lds((const unsigned*)((const char*)(gbase) + (voff)[_i]), (PG8_LAS unsigned*)(lds + (bufoff) + ldsw + _i * 8192), 16, 0, 0); } while (0)
; #define PG8_LDA(dst, b, h) do { _Pragma("unroll") for (int m = 0; m < 4; ++m) _Pragma("unroll") for (int k = 0; k < 2; ++k) dst[m][k] = *(const PG8_LAS bf16x8*)(lds + PG8_SA(b, h) + aoff + m * 2048 + k * 1024); } while (0)
; #define PG8_LDB(dst, b, h) do { _Pragma("unroll") for (int n = 0; n < 2; ++n) _Pragma("unroll") for (int k = 0; k < 2; ++k) dst[n][k] = *(const PG8_LAS bf16x8*)(lds + PG8_SB(b, h) + boff + n * 2048 + k * 1024); } while (0)
; #define PG8_MMA(ai, bj, At, Bt) do { __builtin_amdgcn_s_setprio(1); _Pragma("unroll") for (int m = 0; m < 4; ++m) _Pragma("unroll") for (int n = 0; n < 2; ++n) _Pragma("unroll") for (int k = 0; k < 2; ++k) \
;         acc[ai][bj][m][n] = __builtin_amdgcn_mfma_f32_16x16x32_bf16(Bt[n][k], At[m][k], acc[ai][bj][m][n], 0, 0, 0); __builtin_amdgcn_s_setprio(0); } while (0)
; #define PG8_WAIT_V(n) asm volatile("s_waitcnt vmcnt(" #n ")" ::: "memory")
; #define PG8_WAIT_L(n) asm volatile("s_waitcnt lgkmcnt(" #n ")" ::: "memory")
; template <class Epi, class Sched, bool ALIGN_EPI = false, bool SP2 = false>
; __device__ __forceinline__ void gemm_phase(PG8_LAS unsigned char* lds, const Gemm g, const Sched& S, const Epi& E) {
;     ...
;         const bool has_next = S.next(ui + 1, nxt);
;         const char* nA = has_next ? (const char*)g.A + (size_t)nxt.pm * tstep : cA; const char* nB = has_next ? (const char*)g.Bt + (size_t)nxt.pn * tstep : cB;
;         for (int t = 0; t < nt; t += 2) {
;             const bool last = (t == nt - 2);
;             const char* a1 = cA + (size_t)(t + 1) * kstep;
;             const char* a2 = last ? nA : cA + (size_t)(t + 2) * kstep; const char* b2 = last ? nB : cB + (size_t)(t + 2) * kstep;
;             const char* a3 = a2 + kstep; const char* b3 = b2 + kstep;
;             if (last && has_next) S.a_ready(nxt);
;             if constexpr (SP2) {
;             PG8_LDB(B0, 0, 0); PG8_LDB(B1, 0, 1); PG8_SCHED; PG8_LDA(At, 0, 0); PG8_STAGE(PG8_SA(1, 0), a1, voffA); PG8_STAGE(PG8_SA(1, 1), a1 + hstep, voffA);
;             PG8_WAIT_V(8); PG8_WAIT_L(0); PG8_BAR; PG8_MMA(0, 0, At, B0); PG8_MMA(0, 1, At, B1); PG8_BAR; PG8_SCHED;
.LBB0_425:
	s_ashr_i32 s47, s46, 31
	s_lshl_b64 s[52:53], s[46:47], 20
	s_add_u32 s72, s98, s52
	s_addc_u32 s73, s99, s53
	s_and_b64 s[52:53], s[38:39], exec
	s_cselect_b32 s47, s73, s17
	s_cselect_b32 s68, s72, s16
	s_ashr_i32 s43, s42, 31
	s_lshl_b64 s[52:53], s[42:43], 20
	s_add_u32 s76, s20, s52
	s_addc_u32 s77, s21, s53
	s_and_b64 s[52:53], s[38:39], exec
	s_cselect_b32 s43, s77, s45
	s_cselect_b32 s69, s76, s44
	s_add_u32 s70, s44, 0x100
	s_addc_u32 s71, s45, 0
	v_lshl_add_u64 v[138:139], s[16:17], 0, v[134:135]
	v_lshl_add_u64 v[140:141], s[16:17], 0, v[136:137]
	s_mov_b32 s52, -2
	s_mov_b64 s[88:89], 0
	s_add_u32 s44, s16, s88
	s_addc_u32 s45, s17, s89
	s_add_u32 s53, s44, 0x100
	s_addc_u32 s78, s45, 0
	s_add_u32 s44, s70, s88
	s_addc_u32 s45, s71, s89
	s_add_i32 s79, 0, 0x10000
	s_cmpk_eq_i32 s88, 0xf00
	s_cselect_b32 s45, s43, s45
	s_cselect_b32 s44, s69, s44
	s_cselect_b32 s95, s47, s78
	s_cselect_b32 s94, s68, s53
	s_add_i32 s53, 0, 0x14000
	v_add_u32_e32 v158, s79, v143
	ds_read_b128 v[146:149], v158
	ds_read_b128 v[150:153], v158 offset:1024
	ds_read_b128 v[154:157], v158 offset:2048
	ds_read_b128 v[158:161], v158 offset:3072
	v_lshl_add_u64 v[202:203], v[138:139], 0, s[88:89]
	v_lshl_add_u64 v[222:223], v[202:203], 0, s[26:27]
	s_add_i32 m0, s23, 0x8000
	global_load_lds_dwordx4 v[222:223], off
	v_lshl_add_u64 v[222:223], v[140:141], 0, s[88:89]
	v_lshl_add_u64 v[232:233], v[222:223], 0, s[26:27]
	s_add_i32 m0, s23, 0xa000
	v_lshl_add_u64 v[202:203], v[202:203], 0, s[28:29]
	global_load_lds_dwordx4 v[232:233], off
	s_add_i32 m0, s23, 0xc000
	s_nop 0
	global_load_lds_dwordx4 v[202:203], off
	v_lshl_add_u64 v[202:203], v[222:223], 0, s[28:29]
	s_add_i32 m0, s23, 0xe000
	s_nop 0
	global_load_lds_dwordx4 v[202:203], off
	s_waitcnt vmcnt(8)
	s_waitcnt lgkmcnt(0)
	s_barrier
	v_mfma_f32_16x16x32_bf16 v[124:127], v[146:149], v[178:181], 0
	v_mfma_f32_16x16x32_bf16 v[120:123], v[154:157], v[178:181], 0
	v_mfma_f32_16x16x32_bf16 v[116:119], v[146:149], v[186:189], 0
	v_mfma_f32_16x16x32_bf16 v[108:111], v[154:157], v[186:189], 0
	v_mfma_f32_16x16x32_bf16 v[100:103], v[146:149], v[194:197], 0
	v_mfma_f32_16x16x32_bf16 v[92:95], v[154:157], v[194:197], 0
	v_mfma_f32_16x16x32_bf16 v[84:87], v[146:149], v[206:209], 0
	v_mfma_f32_16x16x32_bf16 v[76:79], v[154:157], v[206:209], 0
	v_mfma_f32_16x16x32_bf16 v[124:127], v[150:153], v[182:185], v[124:127]
	v_mfma_f32_16x16x32_bf16 v[120:123], v[158:161], v[182:185], v[120:123]
	v_mfma_f32_16x16x32_bf16 v[116:119], v[150:153], v[190:193], v[116:119]
	v_mfma_f32_16x16x32_bf16 v[108:111], v[158:161], v[190:193], v[108:111]
	v_mfma_f32_16x16x32_bf16 v[100:103], v[150:153], v[198:201], v[100:103]
	v_mfma_f32_16x16x32_bf16 v[92:95], v[158:161], v[198:201], v[92:95]
	v_mfma_f32_16x16x32_bf16 v[84:87], v[150:153], v[218:221], v[84:87]
	v_mfma_f32_16x16x32_bf16 v[76:79], v[158:161], v[218:221], v[76:79]
	v_mfma_f32_16x16x32_bf16 v[112:115], v[162:165], v[178:181], 0
	v_mfma_f32_16x16x32_bf16 v[104:107], v[170:173], v[178:181], 0
	v_mfma_f32_16x16x32_bf16 v[96:99], v[162:165], v[186:189], 0
	v_mfma_f32_16x16x32_bf16 v[88:91], v[170:173], v[186:189], 0
	v_mfma_f32_16x16x32_bf16 v[80:83], v[162:165], v[194:197], 0
	v_mfma_f32_16x16x32_bf16 v[72:75], v[170:173], v[194:197], 0
	v_mfma_f32_16x16x32_bf16 v[68:71], v[162:165], v[206:209], 0
	v_mfma_f32_16x16x32_bf16 v[64:67], v[170:173], v[206:209], 0
	v_mfma_f32_16x16x32_bf16 v[112:115], v[166:169], v[182:185], v[112:115]
	v_mfma_f32_16x16x32_bf16 v[104:107], v[174:177], v[182:185], v[104:107]
	v_mfma_f32_16x16x32_bf16 v[96:99], v[166:169], v[190:193], v[96:99]
	v_mfma_f32_16x16x32_bf16 v[88:91], v[174:177], v[190:193], v[88:91]
	v_mfma_f32_16x16x32_bf16 v[80:83], v[166:169], v[198:201], v[80:83]
	v_mfma_f32_16x16x32_bf16 v[72:75], v[174:177], v[198:201], v[72:75]
	v_mfma_f32_16x16x32_bf16 v[68:71], v[166:169], v[218:221], v[68:71]
	v_mfma_f32_16x16x32_bf16 v[64:67], v[174:177], v[218:221], v[64:67]
	s_barrier
; #define PG8_STAGE(bufoff, gbase, voff) do { _Pragma("unroll") for (int _i = 0; _i < 2; ++_i) \
;         __builtin_amdgcn_global_load_lds((const unsigned*)((const char*)(gbase) + (voff)[_i]), (PG8_LAS unsigned*)(lds + (bufoff) + ldsw + _i * 8192), 16, 0, 0); } while (0)
; #define PG8_LDA(dst, b, h) do { _Pragma("unroll") for (int m = 0; m < 4; ++m) _Pragma("unroll") for (int k = 0; k < 2; ++k) dst[m][k] = *(const PG8_LAS bf16x8*)(lds + PG8_SA(b, h) + aoff + m * 2048 + k * 1024); } while (0)
; #define PG8_MMA(ai, bj, At, Bt) do { __builtin_amdgcn_s_setprio(1); _Pragma("unroll") for (int m = 0; m < 4; ++m) _Pragma("unroll") for (int n = 0; n < 2; ++n) _Pragma("unroll") for (int k = 0; k < 2; ++k) \
;         acc[ai][bj][m][n] = __builtin_amdgcn_mfma_f32_16x16x32_bf16(Bt[n][k], At[m][k], acc[ai][bj][m][n], 0, 0, 0); __builtin_amdgcn_s_setprio(0); } while (0)
; #define PG8_WAIT_V(n) asm volatile("s_waitcnt vmcnt(" #n ")" ::: "memory")
; #define PG8_WAIT_L(n) asm volatile("s_waitcnt lgkmcnt(" #n ")" ::: "memory")
; #define PG8_BAR __builtin_amdgcn_s_barrier()
; #define PG8_SCHED __builtin_amdgcn_sched_barrier(0)
; template <class Epi, class Sched, bool ALIGN_EPI = false, bool SP2 = false>
; __device__ __forceinline__ void gemm_phase(PG8_LAS unsigned char* lds, const Gemm g, const Sched& S, const Epi& E) {
;     ...
;             PG8_LDA(At, 0, 1); PG8_STAGE(PG8_SB(0, 0), b2, voffB); PG8_STAGE(PG8_SB(0, 1), b2 + hstep, voffB);
;             PG8_WAIT_V(6); PG8_WAIT_L(0); PG8_BAR; PG8_MMA(1, 0, At, B0); PG8_MMA(1, 1, At, B1); PG8_BAR; PG8_SCHED;
	s_add_i32 s78, s79, s22
	v_lshl_add_u64 v[202:203], s[44:45], 0, v[204:205]
	s_mov_b32 m0, s78
	ds_read_b128 v[178:181], v145 offset:16384
	ds_read_b128 v[182:185], v145 offset:17408
	ds_read_b128 v[186:189], v145 offset:18432
	ds_read_b128 v[190:193], v145 offset:19456
	ds_read_b128 v[194:197], v145 offset:20480
	ds_read_b128 v[198:201], v145 offset:21504
	ds_read_b128 v[206:209], v145 offset:22528
	ds_read_b128 v[218:221], v145 offset:23552
	global_load_lds_dwordx4 v[202:203], off
	s_add_i32 m0, s78, 0x2000
	s_add_u32 s78, s44, 0x80000
	v_lshl_add_u64 v[222:223], s[44:45], 0, v[128:129]
	s_addc_u32 s79, s45, 0
	s_add_i32 s53, s53, s22
	global_load_lds_dwordx4 v[222:223], off
	v_lshl_add_u64 v[232:233], s[78:79], 0, v[204:205]
	s_mov_b32 m0, s53
	s_nop 0
	global_load_lds_dwordx4 v[232:233], off
	v_lshl_add_u64 v[232:233], s[78:79], 0, v[128:129]
	s_add_i32 m0, s53, 0x2000
	s_nop 0
	global_load_lds_dwordx4 v[232:233], off
	s_waitcnt vmcnt(6)
	s_waitcnt lgkmcnt(0)
	s_barrier
	v_mfma_f32_16x16x32_bf16 v[60:63], v[146:149], v[178:181], 0
	v_mfma_f32_16x16x32_bf16 v[56:59], v[154:157], v[178:181], 0
	v_mfma_f32_16x16x32_bf16 v[52:55], v[146:149], v[186:189], 0
	v_mfma_f32_16x16x32_bf16 v[44:47], v[154:157], v[186:189], 0
	v_mfma_f32_16x16x32_bf16 v[36:39], v[146:149], v[194:197], 0
	v_mfma_f32_16x16x32_bf16 v[28:31], v[154:157], v[194:197], 0
	v_mfma_f32_16x16x32_bf16 v[20:23], v[146:149], v[206:209], 0
	v_mfma_f32_16x16x32_bf16 v[12:15], v[154:157], v[206:209], 0
	v_mfma_f32_16x16x32_bf16 v[60:63], v[150:153], v[182:185], v[60:63]
	v_mfma_f32_16x16x32_bf16 v[56:59], v[158:161], v[182:185], v[56:59]
	v_mfma_f32_16x16x32_bf16 v[52:55], v[150:153], v[190:193], v[52:55]
	v_mfma_f32_16x16x32_bf16 v[44:47], v[158:161], v[190:193], v[44:47]
	v_mfma_f32_16x16x32_bf16 v[36:39], v[150:153], v[198:201], v[36:39]
	v_mfma_f32_16x16x32_bf16 v[28:31], v[158:161], v[198:201], v[28:31]
	v_mfma_f32_16x16x32_bf16 v[20:23], v[150:153], v[218:221], v[20:23]
	v_mfma_f32_16x16x32_bf16 v[12:15], v[158:161], v[218:221], v[12:15]
	v_mfma_f32_16x16x32_bf16 v[48:51], v[162:165], v[178:181], 0
	v_mfma_f32_16x16x32_bf16 v[40:43], v[170:173], v[178:181], 0
	v_mfma_f32_16x16x32_bf16 v[32:35], v[162:165], v[186:189], 0
	v_mfma_f32_16x16x32_bf16 v[24:27], v[170:173], v[186:189], 0
	v_mfma_f32_16x16x32_bf16 v[16:19], v[162:165], v[194:197], 0
	v_mfma_f32_16x16x32_bf16 v[8:11], v[170:173], v[194:197], 0
	v_mfma_f32_16x16x32_bf16 v[4:7], v[162:165], v[206:209], 0
	v_mfma_f32_16x16x32_bf16 v[0:3], v[170:173], v[206:209], 0
	v_mfma_f32_16x16x32_bf16 v[48:51], v[166:169], v[182:185], v[48:51]
	v_mfma_f32_16x16x32_bf16 v[40:43], v[174:177], v[182:185], v[40:43]
	v_mfma_f32_16x16x32_bf16 v[32:35], v[166:169], v[190:193], v[32:35]
	v_mfma_f32_16x16x32_bf16 v[24:27], v[174:177], v[190:193], v[24:27]
	v_mfma_f32_16x16x32_bf16 v[16:19], v[166:169], v[198:201], v[16:19]
	v_mfma_f32_16x16x32_bf16 v[8:11], v[174:177], v[198:201], v[8:11]
	v_mfma_f32_16x16x32_bf16 v[4:7], v[166:169], v[218:221], v[4:7]
	v_mfma_f32_16x16x32_bf16 v[0:3], v[174:177], v[218:221], v[0:3]
	s_barrier
	s_branch .Lpl_o
	.p2align 6

; #define PG8_STAGE(bufoff, gbase, voff) do { _Pragma("unroll") for (int _i = 0; _i < 2; ++_i) \
;         __builtin_amdgcn_global_load_lds((const unsigned*)((const char*)(gbase) + (voff)[_i]), (PG8_LAS unsigned*)(lds + (bufoff) + ldsw + _i * 8192), 16, 0, 0); } while (0)
; #define PG8_LDA(dst, b, h) do { _Pragma("unroll") for (int m = 0; m < 4; ++m) _Pragma("unroll") for (int k = 0; k < 2; ++k) dst[m][k] = *(const PG8_LAS bf16x8*)(lds + PG8_SA(b, h) + aoff + m * 2048 + k * 1024); } while (0)
; #define PG8_LDB(dst, b, h) do { _Pragma("unroll") for (int n = 0; n < 2; ++n) _Pragma("unroll") for (int k = 0; k < 2; ++k) dst[n][k] = *(const PG8_LAS bf16x8*)(lds + PG8_SB(b, h) + boff + n * 2048 + k * 1024); } while (0)
; #define PG8_WAIT_V(n) asm volatile("s_waitcnt vmcnt(" #n ")" ::: "memory")
; #define PG8_WAIT_L(n) asm volatile("s_waitcnt lgkmcnt(" #n ")" ::: "memory")
; #define PG8_BAR __builtin_amdgcn_s_barrier()
; #define PG8_SCHED __builtin_amdgcn_sched_barrier(0)
;     __device__ __forceinline__ void operator()(const f32x4 (&acc)[2][2][4][2], const Unit& u, int wr, int wc, int fr, int fq) const {
;     ...
;                 float rsc = sc; if (rsmode == 1) { const float r_ = rs[row0 + ai * HALF + m * 16]; rsc = sc * (ACT == 2 ? r_ * r_ : r_); }
; template <class Epi, class Sched, bool ALIGN_EPI = false, bool SP2 = false>
; __device__ __forceinline__ void gemm_phase(PG8_LAS unsigned char* lds, const Gemm g, const Sched& S, const Epi& E) {
;     ...
;         const bool has_next = S.next(ui + 1, nxt);
;         const char* nA = has_next ? (const char*)g.A + (size_t)nxt.pm * tstep : cA; const char* nB = has_next ? (const char*)g.Bt + (size_t)nxt.pn * tstep : cB;
;         for (int t = 0; t < nt; t += 2) {
;             const bool last = (t == nt - 2);
;             const char* a1 = cA + (size_t)(t + 1) * kstep;
;             const char* a2 = last ? nA : cA + (size_t)(t + 2) * kstep; const char* b2 = last ? nB : cB + (size_t)(t + 2) * kstep;
;             const char* a3 = a2 + kstep; const char* b3 = b2 + kstep;
;             if (last && has_next) S.a_ready(nxt);
;             if constexpr (SP2) {
;             PG8_LDB(B0, 0, 0); PG8_LDB(B1, 0, 1); PG8_SCHED; PG8_LDA(At, 0, 0); PG8_STAGE(PG8_SA(1, 0), a1, voffA); PG8_STAGE(PG8_SA(1, 1), a1 + hstep, voffA);
;             PG8_WAIT_V(8); PG8_WAIT_L(0); PG8_BAR; PG8_MMA(0, 0, At, B0); PG8_MMA(0, 1, At, B1); PG8_BAR; PG8_SCHED;
.LBB0_604:
	s_ashr_i32 s95, s94, 31
	s_lshl_b64 s[16:17], s[94:95], 20
	s_add_u32 s16, s20, s16
	s_addc_u32 s17, s21, s17
	s_and_b64 s[44:45], s[42:43], exec
	s_cselect_b32 s95, s17, s9
	s_cselect_b32 s70, s16, s8
	s_ashr_i32 s7, s6, 31
	s_lshl_b64 s[44:45], s[6:7], 20
	s_add_u32 s44, s22, s44
	s_addc_u32 s45, s23, s45
	s_and_b64 s[52:53], s[42:43], exec
	s_cselect_b32 s7, s45, s11
	s_cselect_b32 s71, s44, s10
	s_add_u32 s79, s10, 0x100
	v_lshl_add_u64 v[138:139], s[8:9], 0, v[134:135]
	v_lshl_add_u64 v[140:141], s[8:9], 0, v[136:137]
	s_addc_u32 s52, s11, 0
	s_mov_b32 s53, -2
	s_mov_b64 vcc, 0
	v_lshl_add_u32 v240, s35, 8, v142
	v_ashrrev_i32_e32 v241, 31, v240
	v_lshl_add_u64 v[240:241], v[240:241], 2, s[88:89]
	global_load_dword v242, v[240:241], off
	global_load_dword v243, v[240:241], off offset:64
	global_load_dword v244, v[240:241], off offset:128
	global_load_dword v245, v[240:241], off offset:192
	global_load_dword v246, v[240:241], off offset:512
	global_load_dword v247, v[240:241], off offset:576
	global_load_dword v248, v[240:241], off offset:640
	global_load_dword v249, v[240:241], off offset:704
	s_add_u32 s10, s8, vcc_lo
	s_addc_u32 s11, s9, vcc_hi
	s_add_u32 s38, s10, 0x100
	s_addc_u32 s39, s11, 0
	s_add_u32 s10, s79, vcc_lo
	s_addc_u32 s11, s52, vcc_hi
	s_add_i32 s78, 0, 0x10000
	s_cmpk_eq_i32 vcc_lo, 0xf00
	s_cselect_b32 s11, s7, s11
	s_cselect_b32 s10, s71, s10
	s_cselect_b32 s69, s95, s39
	s_cselect_b32 s68, s70, s38
	s_add_i32 s92, 0, 0x14000
	v_add_u32_e32 v158, s78, v143
	ds_read_b128 v[146:149], v158
	ds_read_b128 v[150:153], v158 offset:1024
	ds_read_b128 v[154:157], v158 offset:2048
	ds_read_b128 v[158:161], v158 offset:3072
	v_lshl_add_u64 v[202:203], v[140:141], 0, vcc
	v_lshl_add_u64 v[222:223], v[202:203], 0, s[26:27]
	s_add_i32 m0, s37, 0x8000
	global_load_lds_dwordx4 v[222:223], off
	v_lshl_add_u64 v[222:223], v[138:139], 0, vcc
	v_lshl_add_u64 v[232:233], v[222:223], 0, s[26:27]
	s_add_i32 m0, s37, 0xa000
	v_lshl_add_u64 v[202:203], v[202:203], 0, s[28:29]
	global_load_lds_dwordx4 v[232:233], off
	s_add_i32 m0, s37, 0xc000
	s_nop 0
	global_load_lds_dwordx4 v[202:203], off
	v_lshl_add_u64 v[202:203], v[222:223], 0, s[28:29]
	s_add_i32 m0, s37, 0xe000
	s_nop 0
	global_load_lds_dwordx4 v[202:203], off
	s_waitcnt vmcnt(8)
	s_waitcnt lgkmcnt(0)
	s_barrier
	v_mfma_f32_16x16x32_bf16 v[124:127], v[146:149], v[178:181], 0
	v_mfma_f32_16x16x32_bf16 v[120:123], v[154:157], v[178:181], 0
	v_mfma_f32_16x16x32_bf16 v[108:111], v[146:149], v[186:189], 0
	v_mfma_f32_16x16x32_bf16 v[104:107], v[154:157], v[186:189], 0
	v_mfma_f32_16x16x32_bf16 v[92:95], v[146:149], v[194:197], 0
	v_mfma_f32_16x16x32_bf16 v[88:91], v[154:157], v[194:197], 0
	v_mfma_f32_16x16x32_bf16 v[76:79], v[146:149], v[206:209], 0
	v_mfma_f32_16x16x32_bf16 v[72:75], v[154:157], v[206:209], 0
	v_mfma_f32_16x16x32_bf16 v[124:127], v[150:153], v[182:185], v[124:127]
	v_mfma_f32_16x16x32_bf16 v[120:123], v[158:161], v[182:185], v[120:123]
	v_mfma_f32_16x16x32_bf16 v[108:111], v[150:153], v[190:193], v[108:111]
	v_mfma_f32_16x16x32_bf16 v[104:107], v[158:161], v[190:193], v[104:107]
	v_mfma_f32_16x16x32_bf16 v[92:95], v[150:153], v[198:201], v[92:95]
	v_mfma_f32_16x16x32_bf16 v[88:91], v[158:161], v[198:201], v[88:91]
	v_mfma_f32_16x16x32_bf16 v[76:79], v[150:153], v[218:221], v[76:79]
	v_mfma_f32_16x16x32_bf16 v[72:75], v[158:161], v[218:221], v[72:75]
	v_mfma_f32_16x16x32_bf16 v[116:119], v[162:165], v[178:181], 0
	v_mfma_f32_16x16x32_bf16 v[112:115], v[170:173], v[178:181], 0
	v_mfma_f32_16x16x32_bf16 v[100:103], v[162:165], v[186:189], 0
	v_mfma_f32_16x16x32_bf16 v[96:99], v[170:173], v[186:189], 0
	v_mfma_f32_16x16x32_bf16 v[84:87], v[162:165], v[194:197], 0
	v_mfma_f32_16x16x32_bf16 v[80:83], v[170:173], v[194:197], 0
	v_mfma_f32_16x16x32_bf16 v[68:71], v[162:165], v[206:209], 0
	v_mfma_f32_16x16x32_bf16 v[64:67], v[170:173], v[206:209], 0
	v_mfma_f32_16x16x32_bf16 v[116:119], v[166:169], v[182:185], v[116:119]
	v_mfma_f32_16x16x32_bf16 v[112:115], v[174:177], v[182:185], v[112:115]
	v_mfma_f32_16x16x32_bf16 v[100:103], v[166:169], v[190:193], v[100:103]
	v_mfma_f32_16x16x32_bf16 v[96:99], v[174:177], v[190:193], v[96:99]
	v_mfma_f32_16x16x32_bf16 v[84:87], v[166:169], v[198:201], v[84:87]
	v_mfma_f32_16x16x32_bf16 v[80:83], v[174:177], v[198:201], v[80:83]
	v_mfma_f32_16x16x32_bf16 v[68:71], v[166:169], v[218:221], v[68:71]
	v_mfma_f32_16x16x32_bf16 v[64:67], v[174:177], v[218:221], v[64:67]
	s_barrier
; #define PG8_STAGE(bufoff, gbase, voff) do { _Pragma("unroll") for (int _i = 0; _i < 2; ++_i) \
;         __builtin_amdgcn_global_load_lds((const unsigned*)((const char*)(gbase) + (voff)[_i]), (PG8_LAS unsigned*)(lds + (bufoff) + ldsw + _i * 8192), 16, 0, 0); } while (0)
; #define PG8_LDA(dst, b, h) do { _Pragma("unroll") for (int m = 0; m < 4; ++m) _Pragma("unroll") for (int k = 0; k < 2; ++k) dst[m][k] = *(const PG8_LAS bf16x8*)(lds + PG8_SA(b, h) + aoff + m * 2048 + k * 1024); } while (0)
; #define PG8_MMA(ai, bj, At, Bt) do { __builtin_amdgcn_s_setprio(1); _Pragma("unroll") for (int m = 0; m < 4; ++m) _Pragma("unroll") for (int n = 0; n < 2; ++n) _Pragma("unroll") for (int k = 0; k < 2; ++k) \
;         acc[ai][bj][m][n] = __builtin_amdgcn_mfma_f32_16x16x32_bf16(Bt[n][k], At[m][k], acc[ai][bj][m][n], 0, 0, 0); __builtin_amdgcn_s_setprio(0); } while (0)
; #define PG8_WAIT_V(n) asm volatile("s_waitcnt vmcnt(" #n ")" ::: "memory")
; #define PG8_WAIT_L(n) asm volatile("s_waitcnt lgkmcnt(" #n ")" ::: "memory")
; #define PG8_BAR __builtin_amdgcn_s_barrier()
; #define PG8_SCHED __builtin_amdgcn_sched_barrier(0)
; template <class Epi, class Sched, bool ALIGN_EPI = false, bool SP2 = false>
; __device__ __forceinline__ void gemm_phase(PG8_LAS unsigned char* lds, const Gemm g, const Sched& S, const Epi& E) {
;     ...
;             PG8_LDA(At, 0, 1); PG8_STAGE(PG8_SB(0, 0), b2, voffB); PG8_STAGE(PG8_SB(0, 1), b2 + hstep, voffB);
;             PG8_WAIT_V(6); PG8_WAIT_L(0); PG8_BAR; PG8_MMA(1, 0, At, B0); PG8_MMA(1, 1, At, B1); PG8_BAR; PG8_SCHED;
	s_add_i32 s38, s78, s36
	v_lshl_add_u64 v[202:203], s[10:11], 0, v[204:205]
	s_mov_b32 m0, s38
	ds_read_b128 v[178:181], v145 offset:16384
	ds_read_b128 v[182:185], v145 offset:17408
	ds_read_b128 v[186:189], v145 offset:18432
	ds_read_b128 v[190:193], v145 offset:19456
	ds_read_b128 v[194:197], v145 offset:20480
	ds_read_b128 v[198:201], v145 offset:21504
	ds_read_b128 v[206:209], v145 offset:22528
	ds_read_b128 v[218:221], v145 offset:23552
	global_load_lds_dwordx4 v[202:203], off
	s_add_i32 m0, s38, 0x2000
	s_add_u32 s38, s10, 0x80000
	v_lshl_add_u64 v[222:223], s[10:11], 0, v[128:129]
	s_addc_u32 s39, s11, 0
	s_add_i32 s78, s92, s36
	global_load_lds_dwordx4 v[222:223], off
	v_lshl_add_u64 v[232:233], s[38:39], 0, v[204:205]
	s_mov_b32 m0, s78
	s_nop 0
	global_load_lds_dwordx4 v[232:233], off
	v_lshl_add_u64 v[232:233], s[38:39], 0, v[128:129]
	s_add_i32 m0, s78, 0x2000
	s_nop 0
	global_load_lds_dwordx4 v[232:233], off
	s_waitcnt vmcnt(6)
	s_waitcnt lgkmcnt(0)
	s_barrier
	v_mfma_f32_16x16x32_bf16 v[60:63], v[146:149], v[178:181], 0
	v_mfma_f32_16x16x32_bf16 v[56:59], v[154:157], v[178:181], 0
	v_mfma_f32_16x16x32_bf16 v[44:47], v[146:149], v[186:189], 0
	v_mfma_f32_16x16x32_bf16 v[40:43], v[154:157], v[186:189], 0
	v_mfma_f32_16x16x32_bf16 v[28:31], v[146:149], v[194:197], 0
	v_mfma_f32_16x16x32_bf16 v[24:27], v[154:157], v[194:197], 0
	v_mfma_f32_16x16x32_bf16 v[12:15], v[146:149], v[206:209], 0
	v_mfma_f32_16x16x32_bf16 v[8:11], v[154:157], v[206:209], 0
	v_mfma_f32_16x16x32_bf16 v[60:63], v[150:153], v[182:185], v[60:63]
	v_mfma_f32_16x16x32_bf16 v[56:59], v[158:161], v[182:185], v[56:59]
	v_mfma_f32_16x16x32_bf16 v[44:47], v[150:153], v[190:193], v[44:47]
	v_mfma_f32_16x16x32_bf16 v[40:43], v[158:161], v[190:193], v[40:43]
	v_mfma_f32_16x16x32_bf16 v[28:31], v[150:153], v[198:201], v[28:31]
	v_mfma_f32_16x16x32_bf16 v[24:27], v[158:161], v[198:201], v[24:27]
	v_mfma_f32_16x16x32_bf16 v[12:15], v[150:153], v[218:221], v[12:15]
	v_mfma_f32_16x16x32_bf16 v[8:11], v[158:161], v[218:221], v[8:11]
	v_mfma_f32_16x16x32_bf16 v[52:55], v[162:165], v[178:181], 0
	v_mfma_f32_16x16x32_bf16 v[48:51], v[170:173], v[178:181], 0
	v_mfma_f32_16x16x32_bf16 v[36:39], v[162:165], v[186:189], 0
	v_mfma_f32_16x16x32_bf16 v[32:35], v[170:173], v[186:189], 0
	v_mfma_f32_16x16x32_bf16 v[20:23], v[162:165], v[194:197], 0
	v_mfma_f32_16x16x32_bf16 v[16:19], v[170:173], v[194:197], 0
	v_mfma_f32_16x16x32_bf16 v[4:7], v[162:165], v[206:209], 0
	v_mfma_f32_16x16x32_bf16 v[0:3], v[170:173], v[206:209], 0
	v_mfma_f32_16x16x32_bf16 v[52:55], v[166:169], v[182:185], v[52:55]
	v_mfma_f32_16x16x32_bf16 v[48:51], v[174:177], v[182:185], v[48:51]
	v_mfma_f32_16x16x32_bf16 v[36:39], v[166:169], v[190:193], v[36:39]
	v_mfma_f32_16x16x32_bf16 v[32:35], v[174:177], v[190:193], v[32:35]
	v_mfma_f32_16x16x32_bf16 v[20:23], v[166:169], v[198:201], v[20:23]
	v_mfma_f32_16x16x32_bf16 v[16:19], v[174:177], v[198:201], v[16:19]
	v_mfma_f32_16x16x32_bf16 v[4:7], v[166:169], v[218:221], v[4:7]
	v_mfma_f32_16x16x32_bf16 v[0:3], v[174:177], v[218:221], v[0:3]
	s_barrier
	s_branch .Lpl_up
	.p2align 6

; #define PG8_STAGE(bufoff, gbase, voff) do { _Pragma("unroll") for (int _i = 0; _i < 2; ++_i) \
;         __builtin_amdgcn_global_load_lds((const unsigned*)((const char*)(gbase) + (voff)[_i]), (PG8_LAS unsigned*)(lds + (bufoff) + ldsw + _i * 8192), 16, 0, 0); } while (0)
; #define PG8_LDA(dst, b, h) do { _Pragma("unroll") for (int m = 0; m < 4; ++m) _Pragma("unroll") for (int k = 0; k < 2; ++k) dst[m][k] = *(const PG8_LAS bf16x8*)(lds + PG8_SA(b, h) + aoff + m * 2048 + k * 1024); } while (0)
; #define PG8_LDB(dst, b, h) do { _Pragma("unroll") for (int n = 0; n < 2; ++n) _Pragma("unroll") for (int k = 0; k < 2; ++k) dst[n][k] = *(const PG8_LAS bf16x8*)(lds + PG8_SB(b, h) + boff + n * 2048 + k * 1024); } while (0)
; #define PG8_MMA(ai, bj, At, Bt) do { __builtin_amdgcn_s_setprio(1); _Pragma("unroll") for (int m = 0; m < 4; ++m) _Pragma("unroll") for (int n = 0; n < 2; ++n) _Pragma("unroll") for (int k = 0; k < 2; ++k) \
;         acc[ai][bj][m][n] = __builtin_amdgcn_mfma_f32_16x16x32_bf16(Bt[n][k], At[m][k], acc[ai][bj][m][n], 0, 0, 0); __builtin_amdgcn_s_setprio(0); } while (0)
; #define PG8_WAIT_V(n) asm volatile("s_waitcnt vmcnt(" #n ")" ::: "memory")
; #define PG8_WAIT_L(n) asm volatile("s_waitcnt lgkmcnt(" #n ")" ::: "memory")
; template <class Epi, class Sched, bool ALIGN_EPI = false, bool SP2 = false>
; __device__ __forceinline__ void gemm_phase(PG8_LAS unsigned char* lds, const Gemm g, const Sched& S, const Epi& E) {
;     ...
;         const bool has_next = S.next(ui + 1, nxt);
;         const char* nA = has_next ? (const char*)g.A + (size_t)nxt.pm * tstep : cA; const char* nB = has_next ? (const char*)g.Bt + (size_t)nxt.pn * tstep : cB;
;         for (int t = 0; t < nt; t += 2) {
;             const bool last = (t == nt - 2);
;             const char* a1 = cA + (size_t)(t + 1) * kstep;
;             const char* a2 = last ? nA : cA + (size_t)(t + 2) * kstep; const char* b2 = last ? nB : cB + (size_t)(t + 2) * kstep;
;             const char* a3 = a2 + kstep; const char* b3 = b2 + kstep;
;             if (last && has_next) S.a_ready(nxt);
;             if constexpr (SP2) {
;             PG8_LDB(B0, 0, 0); PG8_LDB(B1, 0, 1); PG8_SCHED; PG8_LDA(At, 0, 0); PG8_STAGE(PG8_SA(1, 0), a1, voffA); PG8_STAGE(PG8_SA(1, 1), a1 + hstep, voffA);
;             PG8_WAIT_V(8); PG8_WAIT_L(0); PG8_BAR; PG8_MMA(0, 0, At, B0); PG8_MMA(0, 1, At, B1); PG8_BAR; PG8_SCHED;
.LBB0_701:
	s_ashr_i32 s47, s46, 31
	s_lshl_b64 s[38:39], s[46:47], 22
	s_add_u32 s72, s20, s38
	s_addc_u32 s73, s21, s39
	s_and_b64 s[38:39], s[40:41], exec
	s_cselect_b32 s47, s73, s17
	s_cselect_b32 s70, s72, s16
	s_ashr_i32 s43, s42, 31
	s_lshl_b64 s[38:39], s[42:43], 22
	s_add_u32 s76, s23, s38
	s_addc_u32 s77, s34, s39
	s_and_b64 s[38:39], s[40:41], exec
	s_cselect_b32 s43, s77, s45
	s_cselect_b32 s71, s76, s44
	s_add_u32 s97, s44, 0x100
	s_addc_u32 vcc_lo, s45, 0
	v_lshl_add_u64 v[138:139], s[16:17], 0, v[134:135]
	v_lshl_add_u64 v[140:141], s[16:17], 0, v[136:137]
	s_mov_b32 s52, -2
	s_mov_b64 s[88:89], 0
	s_add_u32 s38, s16, s88
	s_addc_u32 s39, s17, s89
	s_add_u32 s38, s38, 0x100
	s_addc_u32 s39, s39, 0
	s_add_u32 s44, s97, s88
	s_addc_u32 s45, vcc_lo, s89
	s_add_i32 s53, 0, 0x10000
	s_cmpk_eq_i32 s88, 0x3f00
	s_cselect_b32 s45, s43, s45
	s_cselect_b32 s44, s71, s44
	s_cselect_b32 s69, s47, s39
	s_cselect_b32 s68, s70, s38
	s_add_i32 s78, 0, 0x14000
	v_add_u32_e32 v158, s53, v143
	ds_read_b128 v[146:149], v158
	ds_read_b128 v[150:153], v158 offset:1024
	ds_read_b128 v[154:157], v158 offset:2048
	ds_read_b128 v[158:161], v158 offset:3072
	v_lshl_add_u64 v[202:203], v[138:139], 0, s[88:89]
	v_lshl_add_u64 v[222:223], v[202:203], 0, s[26:27]
	s_add_i32 m0, s36, 0x8000
	global_load_lds_dwordx4 v[222:223], off
	v_lshl_add_u64 v[222:223], v[140:141], 0, s[88:89]
	v_lshl_add_u64 v[232:233], v[222:223], 0, s[26:27]
	s_add_i32 m0, s36, 0xa000
	v_lshl_add_u64 v[202:203], v[202:203], 0, s[90:91]
	global_load_lds_dwordx4 v[232:233], off
	s_add_i32 m0, s36, 0xc000
	s_nop 0
	global_load_lds_dwordx4 v[202:203], off
	v_lshl_add_u64 v[202:203], v[222:223], 0, s[90:91]
	s_add_i32 m0, s36, 0xe000
	s_nop 0
	global_load_lds_dwordx4 v[202:203], off
	s_waitcnt vmcnt(8)
	s_waitcnt lgkmcnt(0)
	s_barrier
	v_mfma_f32_16x16x32_bf16 v[124:127], v[146:149], v[178:181], 0
	v_mfma_f32_16x16x32_bf16 v[120:123], v[154:157], v[178:181], 0
	v_mfma_f32_16x16x32_bf16 v[116:119], v[146:149], v[186:189], 0
	v_mfma_f32_16x16x32_bf16 v[108:111], v[154:157], v[186:189], 0
	v_mfma_f32_16x16x32_bf16 v[100:103], v[146:149], v[194:197], 0
	v_mfma_f32_16x16x32_bf16 v[92:95], v[154:157], v[194:197], 0
	v_mfma_f32_16x16x32_bf16 v[84:87], v[146:149], v[206:209], 0
	v_mfma_f32_16x16x32_bf16 v[76:79], v[154:157], v[206:209], 0
	v_mfma_f32_16x16x32_bf16 v[124:127], v[150:153], v[182:185], v[124:127]
	v_mfma_f32_16x16x32_bf16 v[120:123], v[158:161], v[182:185], v[120:123]
	v_mfma_f32_16x16x32_bf16 v[116:119], v[150:153], v[190:193], v[116:119]
	v_mfma_f32_16x16x32_bf16 v[108:111], v[158:161], v[190:193], v[108:111]
	v_mfma_f32_16x16x32_bf16 v[100:103], v[150:153], v[198:201], v[100:103]
	v_mfma_f32_16x16x32_bf16 v[92:95], v[158:161], v[198:201], v[92:95]
	v_mfma_f32_16x16x32_bf16 v[84:87], v[150:153], v[218:221], v[84:87]
	v_mfma_f32_16x16x32_bf16 v[76:79], v[158:161], v[218:221], v[76:79]
	v_mfma_f32_16x16x32_bf16 v[112:115], v[162:165], v[178:181], 0
	v_mfma_f32_16x16x32_bf16 v[104:107], v[170:173], v[178:181], 0
	v_mfma_f32_16x16x32_bf16 v[96:99], v[162:165], v[186:189], 0
	v_mfma_f32_16x16x32_bf16 v[88:91], v[170:173], v[186:189], 0
	v_mfma_f32_16x16x32_bf16 v[80:83], v[162:165], v[194:197], 0
	v_mfma_f32_16x16x32_bf16 v[72:75], v[170:173], v[194:197], 0
	v_mfma_f32_16x16x32_bf16 v[68:71], v[162:165], v[206:209], 0
	v_mfma_f32_16x16x32_bf16 v[64:67], v[170:173], v[206:209], 0
	v_mfma_f32_16x16x32_bf16 v[112:115], v[166:169], v[182:185], v[112:115]
	v_mfma_f32_16x16x32_bf16 v[104:107], v[174:177], v[182:185], v[104:107]
	v_mfma_f32_16x16x32_bf16 v[96:99], v[166:169], v[190:193], v[96:99]
	v_mfma_f32_16x16x32_bf16 v[88:91], v[174:177], v[190:193], v[88:91]
	v_mfma_f32_16x16x32_bf16 v[80:83], v[166:169], v[198:201], v[80:83]
	v_mfma_f32_16x16x32_bf16 v[72:75], v[174:177], v[198:201], v[72:75]
	v_mfma_f32_16x16x32_bf16 v[68:71], v[166:169], v[218:221], v[68:71]
	v_mfma_f32_16x16x32_bf16 v[64:67], v[174:177], v[218:221], v[64:67]
	s_barrier
; #define PG8_STAGE(bufoff, gbase, voff) do { _Pragma("unroll") for (int _i = 0; _i < 2; ++_i) \
;         __builtin_amdgcn_global_load_lds((const unsigned*)((const char*)(gbase) + (voff)[_i]), (PG8_LAS unsigned*)(lds + (bufoff) + ldsw + _i * 8192), 16, 0, 0); } while (0)
; #define PG8_LDA(dst, b, h) do { _Pragma("unroll") for (int m = 0; m < 4; ++m) _Pragma("unroll") for (int k = 0; k < 2; ++k) dst[m][k] = *(const PG8_LAS bf16x8*)(lds + PG8_SA(b, h) + aoff + m * 2048 + k * 1024); } while (0)
; #define PG8_MMA(ai, bj, At, Bt) do { __builtin_amdgcn_s_setprio(1); _Pragma("unroll") for (int m = 0; m < 4; ++m) _Pragma("unroll") for (int n = 0; n < 2; ++n) _Pragma("unroll") for (int k = 0; k < 2; ++k) \
;         acc[ai][bj][m][n] = __builtin_amdgcn_mfma_f32_16x16x32_bf16(Bt[n][k], At[m][k], acc[ai][bj][m][n], 0, 0, 0); __builtin_amdgcn_s_setprio(0); } while (0)
; #define PG8_WAIT_V(n) asm volatile("s_waitcnt vmcnt(" #n ")" ::: "memory")
; #define PG8_WAIT_L(n) asm volatile("s_waitcnt lgkmcnt(" #n ")" ::: "memory")
; #define PG8_BAR __builtin_amdgcn_s_barrier()
; #define PG8_SCHED __builtin_amdgcn_sched_barrier(0)
; template <class Epi, class Sched, bool ALIGN_EPI = false, bool SP2 = false>
; __device__ __forceinline__ void gemm_phase(PG8_LAS unsigned char* lds, const Gemm g, const Sched& S, const Epi& E) {
;     ...
;             PG8_LDA(At, 0, 1); PG8_STAGE(PG8_SB(0, 0), b2, voffB); PG8_STAGE(PG8_SB(0, 1), b2 + hstep, voffB);
;             PG8_WAIT_V(6); PG8_WAIT_L(0); PG8_BAR; PG8_MMA(1, 0, At, B0); PG8_MMA(1, 1, At, B1); PG8_BAR; PG8_SCHED;
	s_add_i32 s38, s53, s35
	v_lshl_add_u64 v[202:203], s[44:45], 0, v[204:205]
	s_mov_b32 m0, s38
	ds_read_b128 v[178:181], v145 offset:16384
	ds_read_b128 v[182:185], v145 offset:17408
	ds_read_b128 v[186:189], v145 offset:18432
	ds_read_b128 v[190:193], v145 offset:19456
	ds_read_b128 v[194:197], v145 offset:20480
	ds_read_b128 v[198:201], v145 offset:21504
	ds_read_b128 v[206:209], v145 offset:22528
	ds_read_b128 v[218:221], v145 offset:23552
	global_load_lds_dwordx4 v[202:203], off
	s_add_i32 m0, s38, 0x2000
	s_add_u32 s38, s44, 0x200000
	v_lshl_add_u64 v[222:223], s[44:45], 0, v[128:129]
	s_addc_u32 s39, s45, 0
	s_add_i32 s53, s78, s35
	global_load_lds_dwordx4 v[222:223], off
	v_lshl_add_u64 v[232:233], s[38:39], 0, v[204:205]
	s_mov_b32 m0, s53
	s_nop 0
	global_load_lds_dwordx4 v[232:233], off
	v_lshl_add_u64 v[232:233], s[38:39], 0, v[128:129]
	s_add_i32 m0, s53, 0x2000
	s_nop 0
	global_load_lds_dwordx4 v[232:233], off
	s_waitcnt vmcnt(6)
	s_waitcnt lgkmcnt(0)
	s_barrier
	v_mfma_f32_16x16x32_bf16 v[60:63], v[146:149], v[178:181], 0
	v_mfma_f32_16x16x32_bf16 v[56:59], v[154:157], v[178:181], 0
	v_mfma_f32_16x16x32_bf16 v[52:55], v[146:149], v[186:189], 0
	v_mfma_f32_16x16x32_bf16 v[44:47], v[154:157], v[186:189], 0
	v_mfma_f32_16x16x32_bf16 v[36:39], v[146:149], v[194:197], 0
	v_mfma_f32_16x16x32_bf16 v[28:31], v[154:157], v[194:197], 0
	v_mfma_f32_16x16x32_bf16 v[20:23], v[146:149], v[206:209], 0
	v_mfma_f32_16x16x32_bf16 v[12:15], v[154:157], v[206:209], 0
	v_mfma_f32_16x16x32_bf16 v[60:63], v[150:153], v[182:185], v[60:63]
	v_mfma_f32_16x16x32_bf16 v[56:59], v[158:161], v[182:185], v[56:59]
	v_mfma_f32_16x16x32_bf16 v[52:55], v[150:153], v[190:193], v[52:55]
	v_mfma_f32_16x16x32_bf16 v[44:47], v[158:161], v[190:193], v[44:47]
	v_mfma_f32_16x16x32_bf16 v[36:39], v[150:153], v[198:201], v[36:39]
	v_mfma_f32_16x16x32_bf16 v[28:31], v[158:161], v[198:201], v[28:31]
	v_mfma_f32_16x16x32_bf16 v[20:23], v[150:153], v[218:221], v[20:23]
	v_mfma_f32_16x16x32_bf16 v[12:15], v[158:161], v[218:221], v[12:15]
	v_mfma_f32_16x16x32_bf16 v[48:51], v[162:165], v[178:181], 0
	v_mfma_f32_16x16x32_bf16 v[40:43], v[170:173], v[178:181], 0
	v_mfma_f32_16x16x32_bf16 v[32:35], v[162:165], v[186:189], 0
	v_mfma_f32_16x16x32_bf16 v[24:27], v[170:173], v[186:189], 0
	v_mfma_f32_16x16x32_bf16 v[16:19], v[162:165], v[194:197], 0
	v_mfma_f32_16x16x32_bf16 v[8:11], v[170:173], v[194:197], 0
	v_mfma_f32_16x16x32_bf16 v[4:7], v[162:165], v[206:209], 0
	v_mfma_f32_16x16x32_bf16 v[0:3], v[170:173], v[206:209], 0
	v_mfma_f32_16x16x32_bf16 v[48:51], v[166:169], v[182:185], v[48:51]
	v_mfma_f32_16x16x32_bf16 v[40:43], v[174:177], v[182:185], v[40:43]
	v_mfma_f32_16x16x32_bf16 v[32:35], v[166:169], v[190:193], v[32:35]
	v_mfma_f32_16x16x32_bf16 v[24:27], v[174:177], v[190:193], v[24:27]
	v_mfma_f32_16x16x32_bf16 v[16:19], v[166:169], v[198:201], v[16:19]
	v_mfma_f32_16x16x32_bf16 v[8:11], v[174:177], v[198:201], v[8:11]
	v_mfma_f32_16x16x32_bf16 v[4:7], v[166:169], v[218:221], v[4:7]
	v_mfma_f32_16x16x32_bf16 v[0:3], v[174:177], v[218:221], v[0:3]
	s_barrier
	s_branch .Lpl_down
	.p2align 6
